# v7: P3 role interleave - odd XCDs run S5 pass1 + weight transposes first and attention second (even XCDs keep the order), on top of v5
# baseline (speedup 1.0000x reference)
.LBB0_398:
	s_or_b64 exec, exec, s[2:3]
	s_waitcnt lgkmcnt(0)
	s_barrier
	s_mov_b32 s99, 0
.Lp3_again:
	s_load_dwordx8 s[56:63], s[90:91], 0x50
	s_load_dwordx2 s[88:89], s[90:91], 0xc0
	s_load_dwordx2 s[2:3], s[90:91], 0xa8
	s_load_dwordx4 s[68:71], s[90:91], 0x70
	s_load_dwordx4 s[64:67], s[90:91], 0x98
	s_cmpk_lt_i32 s85, 0x200
	s_cselect_b64 s[0:1], -1, 0
	v_mov_b32_e32 v128, v223
	s_waitcnt lgkmcnt(0)
	v_writelane_b32 v250, s2, 17
	s_cmpk_gt_i32 s85, 0x1ff
	s_nop 0
	v_writelane_b32 v250, s3, 18
	v_writelane_b32 v250, s0, 19
	s_nop 1
	v_writelane_b32 v250, s1, 20
	s_cbranch_scc1 .LBB0_439
	s_cmp_lg_u32 s99, 0
	s_cbranch_scc1 .Lp3_att
	s_bitcmp1_b32 s85, 0
	s_cbranch_scc0 .Lp3_att
	s_mov_b32 s99, 1
	s_branch .LBB0_439
.Lp3_att:
	v_readlane_b32 s0, v250, 11
	v_and_b32_e32 v1, 15, v128
	v_lshl_add_u32 v6, v1, 4, 0
	v_add_u32_e32 v0, s0, v128
	v_lshlrev_b32_e32 v130, 3, v1
	v_ashrrev_i32_e32 v129, 4, v0
	v_add_u32_e32 v1, 0x200, v0
	v_add_u32_e32 v2, 0x400, v0
	v_add_u32_e32 v3, 0x600, v0
	v_add_u32_e32 v4, 0x800, v0
	v_add_u32_e32 v5, 0xa00, v0
	v_add_u32_e32 v13, 0xc00, v0
	v_add_u32_e32 v15, 0xe00, v0
	v_and_b32_e32 v173, 0xff, v0
	v_ashrrev_i32_e32 v0, 5, v0
	v_and_b32_e32 v134, -8, v0
	v_ashrrev_i32_e32 v0, 5, v1
	v_and_b32_e32 v136, -8, v0
	v_ashrrev_i32_e32 v0, 5, v2
	v_and_b32_e32 v138, -8, v0
	v_ashrrev_i32_e32 v0, 5, v3
	v_and_b32_e32 v140, -8, v0
	v_ashrrev_i32_e32 v0, 5, v4
	v_and_b32_e32 v142, -8, v0
	v_ashrrev_i32_e32 v0, 5, v5
	v_and_b32_e32 v144, -8, v0
	v_ashrrev_i32_e32 v0, 5, v13
	v_ashrrev_i32_e32 v151, 4, v2
	v_and_b32_e32 v146, -8, v0
	v_ashrrev_i32_e32 v0, 5, v15
	v_ashrrev_i32_e32 v2, 5, v128
	v_and_b32_e32 v148, -8, v0
	v_lshlrev_b32_e32 v0, 3, v2
	v_lshl_add_u32 v150, v2, 4, 0
	v_lshlrev_b32_e32 v2, 2, v2
	v_ashrrev_i32_e32 v169, 4, v4
	v_and_b32_e32 v174, 31, v128
	v_or_b32_e32 v4, 2, v2
	v_cmp_gt_i32_e64 s[24:25], v4, v174
	v_or_b32_e32 v4, 3, v2
	v_cmp_gt_i32_e64 s[26:27], v4, v174
	v_add_u32_e32 v4, 8, v2
	v_cmp_gt_i32_e64 s[28:29], v4, v174
	v_add_u32_e32 v4, 9, v2
	v_cmp_gt_i32_e64 s[30:31], v4, v174
	v_add_u32_e32 v4, 10, v2
	v_cmp_gt_i32_e64 s[34:35], v4, v174
	v_add_u32_e32 v4, 11, v2
	v_cmp_gt_i32_e64 s[36:37], v4, v174
	v_add_u32_e32 v4, 16, v2
	v_cmp_gt_i32_e64 s[38:39], v4, v174
	v_add_u32_e32 v4, 17, v2
	v_cmp_gt_i32_e64 s[40:41], v4, v174
	v_add_u32_e32 v4, 18, v2
	v_cmp_gt_i32_e64 s[42:43], v4, v174
	v_add_u32_e32 v4, 19, v2
	v_cmp_gt_i32_e64 s[44:45], v4, v174
	v_add_u32_e32 v4, 24, v2
	s_add_u32 s90, s88, 0x25000000
	s_movk_i32 s0, 0x7f
	v_ashrrev_i32_e32 v131, 4, v1
	v_ashrrev_i32_e32 v168, 4, v3
	v_ashrrev_i32_e32 v170, 4, v5
	v_ashrrev_i32_e32 v171, 4, v13
	v_ashrrev_i32_e32 v172, 4, v15
	v_add_u32_e32 v3, 64, v204
	v_cmp_gt_i32_e64 s[46:47], v4, v174
	v_add_u32_e32 v4, 25, v2
	s_addc_u32 s91, s89, 0
	v_cmp_lt_i32_e64 s[2:3], s0, v129
	v_cmp_lt_i32_e64 s[4:5], s0, v131
	v_cmp_lt_i32_e64 s[6:7], s0, v151
	v_cmp_lt_i32_e64 s[8:9], s0, v168
	v_cmp_lt_i32_e64 s[10:11], s0, v169
	v_cmp_lt_i32_e64 s[12:13], s0, v170
	v_cmp_lt_i32_e64 s[14:15], s0, v171
	v_cmp_lt_i32_e64 s[16:17], s0, v172
	v_cmp_lt_u32_e64 s[18:19], s0, v173
	s_movk_i32 s0, 0x208
	v_cmp_lt_i32_e32 vcc, v205, v3
	v_cmp_gt_i32_e64 s[48:49], v4, v174
	v_add_u32_e32 v4, 26, v2
	s_add_u32 s92, s88, 0x26000000
	v_mul_lo_u32 v18, v134, s0
	v_mul_lo_u32 v19, v136, s0
	v_mul_lo_u32 v20, v138, s0
	v_mul_lo_u32 v21, v140, s0
	v_mul_lo_u32 v22, v142, s0
	v_mul_lo_u32 v23, v144, s0
	v_mul_lo_u32 v13, v146, s0
	v_mul_lo_u32 v15, v148, s0
	v_readlane_b32 s0, v250, 4
	v_ashrrev_i32_e32 v1, 31, v0
	v_cndmask_b32_e32 v3, v223, v205, vcc
	v_cmp_gt_i32_e64 s[50:51], v4, v174
	v_add_u32_e32 v4, 27, v2
	s_addc_u32 s93, s89, 0
	s_add_i32 s33, 0, 0x11000
	s_lshr_b32 s81, s0, 7
	s_and_b32 s72, s0, 64
	v_lshlrev_b32_e32 v175, 2, v3
	v_ashrrev_i32_e32 v3, 31, v2
	v_cmp_gt_i32_e64 s[52:53], v4, v174
	v_mul_u32_u24_e32 v24, 0x208, v174
	v_lshl_add_u64 v[4:5], v[0:1], 1, s[88:89]
	s_mov_b64 s[0:1], 0x21000000
	s_movk_i32 s79, 0x110
	v_lshl_add_u64 v[152:153], v[4:5], 0, s[0:1]
	v_add3_u32 v176, s33, v0, v24
	v_lshl_add_u64 v[0:1], s[88:89], 0, v[2:3]
	s_mov_b64 s[0:1], 0x2b000000
	v_mul_lo_u32 v7, v129, s79
	v_mul_lo_u32 v8, v131, s79
	v_mul_lo_u32 v9, v151, s79
	v_mul_lo_u32 v10, v168, s79
	v_mul_lo_u32 v11, v169, s79
	v_mul_lo_u32 v12, v170, s79
	v_mul_lo_u32 v14, v171, s79
	v_mul_lo_u32 v16, v172, s79
	v_lshl_add_u32 v17, v173, 1, s33
	v_lshl_add_u64 v[154:155], v[0:1], 0, s[0:1]
	v_lshl_add_u64 v[0:1], v[2:3], 1, s[88:89]
	s_mov_b64 s[0:1], 0x33000000
	s_mov_b32 s95, 0
	v_mov_b32_e32 v133, 0
	v_ashrrev_i32_e32 v135, 31, v134
	v_ashrrev_i32_e32 v137, 31, v136
	v_ashrrev_i32_e32 v139, 31, v138
	v_ashrrev_i32_e32 v141, 31, v140
	v_ashrrev_i32_e32 v143, 31, v142
	v_ashrrev_i32_e32 v145, 31, v144
	v_ashrrev_i32_e32 v147, 31, v146
	v_ashrrev_i32_e32 v149, 31, v148
	v_cmp_gt_i32_e64 s[20:21], v2, v174
	v_cmp_lt_i32_e64 s[22:23], v2, v174
	s_sub_i32 s73, 0x80, s72
	v_lshl_add_u64 v[156:157], v[0:1], 0, s[0:1]
	v_add_u32_e32 v177, v6, v7
	v_add_u32_e32 v178, v6, v8
	v_add_u32_e32 v179, v6, v9
	v_add_u32_e32 v180, v6, v10
	v_add_u32_e32 v181, v6, v11
	v_add_u32_e32 v182, v6, v12
	v_add_u32_e32 v183, v6, v14
	v_add_u32_e32 v184, v6, v16
	v_add_u32_e32 v185, v17, v18
	v_add_u32_e32 v186, v17, v19
	v_add_u32_e32 v187, v17, v20
	v_add_u32_e32 v188, v17, v21
	v_add_u32_e32 v189, v17, v22
	v_add_u32_e32 v190, v17, v23
	v_add_u32_e32 v191, v17, v13
	v_add_u32_e32 v192, v17, v15
	s_mov_b32 s76, 0x3b808081
	v_mov_b32_e32 v193, 0xff800000
	s_mov_b32 s33, s85
	s_branch .LBB0_401

.LBB0_439:
	s_cmp_eq_u32 s99, 2
	s_cbranch_scc1 .Lp3_done
	v_readlane_b32 s0, v250, 4
	s_cmpk_lt_u32 s0, 0x100
	s_cselect_b64 s[12:13], -1, 0
	s_and_b64 vcc, exec, s[12:13]
	v_readlane_b32 s56, v250, 12
	s_cbranch_vccz .LBB0_455
	s_lshl_b32 s0, s85, 2
	s_or_b32 s14, s56, s0
	s_cmpk_gt_i32 s14, 0x7ff
	s_cbranch_scc1 .LBB0_455
	v_ashrrev_i32_e32 v1, 4, v128
	v_ashrrev_i32_e32 v129, 31, v128
	s_lshl_b32 s1, s74, 2
	s_movk_i32 s2, 0x50
	v_lshlrev_b32_e32 v0, 3, v1
	s_waitcnt vmcnt(31)
	v_mov_b32_e32 v73, 0
	v_lshl_add_u64 v[2:3], v[128:129], 3, s[88:89]
	s_mov_b64 s[6:7], 0x400000
	v_and_b32_e32 v72, 16, v128
	s_add_u32 s16, s88, 0x27000000
	s_waitcnt vmcnt(22)
	v_and_b32_e32 v90, 15, v128
	v_mul_lo_u32 v4, v128, s2
	v_and_b32_e32 v0, 8, v0
	v_readlane_b32 s8, v250, 6
	v_cmp_lt_i32_e64 s[2:3], 1, v1
	v_cmp_gt_i32_e64 s[4:5], 2, v1
	v_and_b32_e32 v1, -16, v128
	v_lshl_add_u64 v[74:75], v[2:3], 0, s[6:7]
	v_lshl_add_u64 v[2:3], s[88:89], 0, v[72:73]
	s_mov_b64 s[6:7], 0x27010000
	s_addc_u32 s17, s89, 0
	v_lshl_add_u32 v5, v0, 2, s8
	v_mul_u32_u24_e32 v6, 0x50, v90
	v_add_u32_e32 v1, s8, v1
	v_lshl_add_u64 v[76:77], v[2:3], 0, s[6:7]
	s_lshl_b32 s6, s85, 4
	s_lshl_b32 s7, s56, 2
	s_add_i32 s24, s6, s7
	s_lshl_b32 s25, s74, 4
	s_add_i32 s26, s0, s56
	s_mov_b32 s27, 0x3fb8aa3b
	s_mov_b32 s28, 0xc2ce8ed0
	s_mov_b32 s19, 0
	s_mov_b32 s29, 0x42b17218
	s_waitcnt vmcnt(21)
	v_mov_b32_e32 v91, 0x7f800000
	s_brev_b32 s30, 18
	s_mov_b32 s31, 0xfe5163ab
	s_mov_b32 s33, 0x3c439041
	s_mov_b32 s34, 0xdb629599
	s_mov_b32 s35, 0xf534ddc0
	s_mov_b32 s36, 0xfc2757d1
	s_mov_b32 s37, 0x4e441529
	s_mov_b32 s38, 0xa2f9836e
	s_mov_b32 s39, 0x3fc90fda
	s_mov_b32 s40, 0x3f22f983
	s_mov_b32 s41, 0xbfc90fda
	s_waitcnt vmcnt(20)
	v_mov_b32_e32 v92, 0x3c0881c4
	s_waitcnt vmcnt(19)
	v_mov_b32_e32 v93, 0xbab64f3b
	s_brev_b32 s42, 1
	s_movk_i32 s43, 0x1f8
	s_waitcnt vmcnt(18)
	v_add_u32_e32 v94, v5, v6
	v_lshlrev_b32_e32 v72, 1, v0
	s_waitcnt vmcnt(17)
	v_add_u32_e32 v95, v1, v6
	v_not_b32_e32 v96, 63
	v_not_b32_e32 v97, 31
	v_mov_b32_e32 v98, 0x7fc00000
	v_add_u32_e32 v99, s8, v4
	s_branch .LBB0_443

.Lp3_done:
	v_readlane_b32 s0, v250, 4
	s_cmpk_lt_u32 s0, 0x100
	s_cselect_b64 s[12:13], -1, 0
	v_readlane_b32 s94, v250, 9
	v_readlane_b32 s95, v250, 10
	v_readlane_b32 s72, v250, 7
	v_readlane_b32 s73, v250, 8
	s_branch .LBB0_813
.Lp3_tail:
	s_cmp_eq_u32 s99, 1
	s_cbranch_scc0 .LBB0_813
	s_mov_b32 s99, 2
	v_readlane_b32 s90, v250, 7
	v_readlane_b32 s91, v250, 8
	s_waitcnt lgkmcnt(0)
	s_barrier
	s_branch .Lp3_again
